# GDN scan: finalizer output stores deferred behind the staging loads and left in flight across the step barrier
# speedup vs baseline: 1.0032x; 1.0032x over previous
.LBB0_442:
	s_lshl_b32 s38, s1, 8
	s_lshl_b32 s1, s37, 5
	v_or_b32_e32 v2, s1, v141
	v_mov_b32_e32 v4, v3
	v_mov_b32_e32 v5, v3
	s_lshl_b32 s21, s36, 12
	s_mov_b32 s39, s9
	v_bitop3_b32 v201, v2, v184, 16 bitop3:0x36
	s_and_b32 s0, s0, 0xc0
	v_mov_b32_e32 v2, v3
	v_mov_b64_e32 v[20:21], v[4:5]
	v_mov_b64_e32 v[8:9], v[4:5]
	v_mov_b64_e32 v[12:13], v[4:5]
	v_mov_b64_e32 v[24:25], v[4:5]
	v_mov_b64_e32 v[32:33], v[4:5]
	v_mov_b64_e32 v[16:17], v[4:5]
	v_mov_b64_e32 v[28:29], v[4:5]
	v_mov_b64_e32 v[36:37], v[4:5]
	v_mov_b64_e32 v[40:41], v[4:5]
	v_mov_b64_e32 v[44:45], v[4:5]
	v_mov_b64_e32 v[64:65], v[4:5]
	v_mov_b64_e32 v[52:53], v[4:5]
	v_mov_b64_e32 v[60:61], v[4:5]
	v_mov_b64_e32 v[56:57], v[4:5]
	v_mov_b64_e32 v[48:49], v[4:5]
	v_mov_b64_e32 v[68:69], v[4:5]
	v_lshl_add_u64 v[150:151], v[142:143], 0, s[38:39]
	v_bitop3_b32 v149, s1, v184, v141 bitop3:0x36
	v_lshl_add_u32 v202, s0, 2, v185
	v_or_b32_e32 v203, s21, v140
	s_mov_b32 s56, 0
	s_mov_b32 s57, 1
	s_lshl_b32 s36, s28, 1
	v_mov_b64_e32 v[18:19], v[2:3]
	v_mov_b64_e32 v[6:7], v[2:3]
	v_mov_b64_e32 v[10:11], v[2:3]
	v_mov_b64_e32 v[22:23], v[2:3]
	v_mov_b64_e32 v[30:31], v[2:3]
	v_mov_b64_e32 v[14:15], v[2:3]
	v_mov_b64_e32 v[26:27], v[2:3]
	v_mov_b64_e32 v[34:35], v[2:3]
	v_mov_b64_e32 v[38:39], v[2:3]
	v_mov_b64_e32 v[42:43], v[2:3]
	v_mov_b64_e32 v[62:63], v[2:3]
	v_mov_b64_e32 v[50:51], v[2:3]
	v_mov_b64_e32 v[58:59], v[2:3]
	v_mov_b64_e32 v[54:55], v[2:3]
	v_mov_b64_e32 v[46:47], v[2:3]
	v_mov_b64_e32 v[66:67], v[2:3]
	s_mov_b32 s29, 0
	s_waitcnt vmcnt(0)
.LBB0_443:
	s_and_b64 vcc, exec, s[24:25]
	s_cbranch_vccnz .Lscan_top_w0
	s_waitcnt vmcnt(4)
	s_branch .Lscan_top_w1

.Lscan_top_w1:
	s_waitcnt lgkmcnt(0)
	s_barrier
	s_andn2_b64 vcc, exec, s[22:23]
	s_cbranch_vccnz .LBB0_445
	s_min_u32 s0, s29, 1
	s_sub_i32 s1, s29, s0
	s_lshl_b32 s0, s0, 6
	v_subrev_u32_e32 v2, s0, v203
	s_and_b32 s0, s1, 1
	v_lshl_add_u32 v205, s0, 10, v199
	ds_read2_b32 v[4:5], v205 offset1:16
	ds_read2_b32 v[120:121], v205 offset0:128 offset1:144
	ds_read2_b32 v[122:123], v205 offset0:64 offset1:80
	ds_read2_b32 v[134:135], v205 offset0:192 offset1:208
	v_lshl_add_u32 v204, s0, 14, v182
	s_waitcnt lgkmcnt(0)
	v_mov_b32_e32 v102, v4
	v_mov_b32_e32 v103, v120
	v_mov_b32_e32 v104, v122
	v_mov_b32_e32 v105, v134
	v_add_u32_e32 v4, v204, v186
	s_waitcnt vmcnt(4)
	v_lshlrev_b32_e32 v114, 16, v170
	v_pk_add_f32 v[136:137], v[102:103], v[104:105]
	ds_read_b128 v[116:119], v4
	ds_read_b128 v[102:105], v183
	v_and_b32_e32 v115, 0xffff0000, v170
	v_mul_f32_e32 v4, 0xbfb8aa3b, v114
	v_exp_f32_e32 v4, v4
	v_mul_f32_e32 v106, 0xbfb8aa3b, v115
	v_exp_f32_e32 v110, v106
	ds_read_b128 v[106:109], v183 offset:16
	v_add_f32_e32 v4, 1.0, v4
	v_rcp_f32_e32 v124, v4
	v_add_f32_e32 v4, 1.0, v110
	v_rcp_f32_e32 v125, v4
	v_add_u32_e32 v4, v204, v188
	ds_read_b128 v[110:113], v4
	s_waitcnt lgkmcnt(3)
	v_lshlrev_b32_e32 v206, 16, v116
	v_pk_mul_f32 v[114:115], v[124:125], v[114:115]
	v_lshlrev_b32_e32 v124, 16, v171
	v_mul_f32_e32 v4, 0xbfb8aa3b, v124
	v_and_b32_e32 v125, 0xffff0000, v171
	v_and_b32_e32 v207, 0xffff0000, v116
	v_exp_f32_e32 v4, v4
	v_mul_f32_e32 v116, 0xbfb8aa3b, v125
	v_exp_f32_e32 v120, v116
	v_lshlrev_b32_e32 v128, 16, v168
	v_add_f32_e32 v4, 1.0, v4
	v_rcp_f32_e32 v126, v4
	v_add_f32_e32 v4, 1.0, v120
	v_rcp_f32_e32 v127, v4
	v_mul_f32_e32 v4, 0xbfb8aa3b, v128
	v_and_b32_e32 v129, 0xffff0000, v168
	v_exp_f32_e32 v4, v4
	v_mul_f32_e32 v120, 0xbfb8aa3b, v129
	v_exp_f32_e32 v120, v120
	v_lshlrev_b32_e32 v168, 16, v169
	v_pk_mul_f32 v[124:125], v[126:127], v[124:125]
	v_add_f32_e32 v4, 1.0, v4
	v_lshlrev_b32_e32 v126, 16, v118
	v_and_b32_e32 v127, 0xffff0000, v118
	v_and_b32_e32 v169, 0xffff0000, v169
	v_mul_f32_e32 v118, 0xbfb8aa3b, v168
	v_rcp_f32_e32 v130, v4
	v_add_f32_e32 v4, 1.0, v120
	v_exp_f32_e32 v118, v118
	v_mul_f32_e32 v120, 0xbfb8aa3b, v169
	v_exp_f32_e32 v120, v120
	v_rcp_f32_e32 v131, v4
	v_add_f32_e32 v4, 1.0, v118
	v_rcp_f32_e32 v170, v4
	v_add_f32_e32 v4, 1.0, v120
	v_mov_b32_e32 v120, v5
	v_mov_b32_e32 v134, v123
	v_pk_mul_f32 v[132:133], v[130:131], v[128:129]
	v_lshlrev_b32_e32 v130, 16, v119
	v_and_b32_e32 v131, 0xffff0000, v119
	v_pk_add_f32 v[118:119], v[120:121], v[134:135]
	v_mov_b32_e32 v121, v136
	v_mov_b32_e32 v120, v118
	v_mov_b32_e32 v136, v119
	v_pk_add_f32 v[118:119], v[120:121], v[136:137]
	v_mov_b64_e32 v[122:123], s[18:19]
	v_pk_fma_f32 v[134:135], v[118:119], s[14:15], v[122:123] op_sel_hi:[1,0,0]
	v_rcp_f32_e32 v171, v4
	v_add_u32_e32 v4, s56, v2
	v_mul_f32_e32 v2, 0x4b800000, v135
	v_cmp_gt_f32_e32 vcc, s51, v135
	v_ashrrev_i32_e32 v5, 31, v4
	v_lshlrev_b64 v[118:119], 11, v[4:5]
	v_cndmask_b32_e32 v2, v135, v2, vcc
	v_rsq_f32_e32 v2, v2
	v_pk_mul_f32 v[128:129], v[170:171], v[168:169]
	v_lshlrev_b32_e32 v116, 16, v117
	v_and_b32_e32 v117, 0xffff0000, v117
	v_mul_f32_e32 v5, 0x45800000, v2
	v_cndmask_b32_e32 v2, v2, v5, vcc
	v_pk_mul_f32 v[168:169], v[2:3], v[206:207] op_sel_hi:[0,1]
	s_waitcnt lgkmcnt(2)
	v_pk_mul_f32 v[168:169], v[102:103], v[168:169]
	v_cmp_gt_f32_e32 vcc, s51, v134
	v_pk_mul_f32 v[114:115], v[114:115], v[168:169]
	v_lshl_add_u64 v[136:137], v[150:151], 0, v[118:119]
	v_cvt_pk_bf16_f32 v168, v114, v115
	v_pk_mul_f32 v[114:115], v[2:3], v[116:117] op_sel_hi:[0,1]
	v_pk_mul_f32 v[114:115], v[104:105], v[114:115]
	ds_read_b128 v[118:121], v183
	v_pk_mul_f32 v[114:115], v[124:125], v[114:115]
	v_pk_mul_f32 v[124:125], v[2:3], v[126:127] op_sel_hi:[0,1]
	s_waitcnt lgkmcnt(2)
	v_pk_mul_f32 v[124:125], v[106:107], v[124:125]
	v_cvt_pk_bf16_f32 v169, v114, v115
	v_pk_mul_f32 v[124:125], v[132:133], v[124:125]
	ds_read_b128 v[114:117], v183 offset:16
	v_cvt_pk_bf16_f32 v170, v124, v125
	v_pk_mul_f32 v[124:125], v[2:3], v[130:131] op_sel_hi:[0,1]
	v_mul_f32_e32 v2, 0x4b800000, v134
	v_cndmask_b32_e32 v2, v134, v2, vcc
	v_rsq_f32_e32 v2, v2
	v_pk_mul_f32 v[124:125], v[108:109], v[124:125]
	v_mul_f32_e32 v5, 0x45800000, v2
	v_pk_mul_f32 v[124:125], v[128:129], v[124:125]
	v_cndmask_b32_e32 v2, v2, v5, vcc
	v_cvt_pk_bf16_f32 v171, v124, v125
	v_lshlrev_b32_e32 v124, 16, v164
	v_mul_f32_e32 v5, 0xbfb8aa3b, v124
	v_and_b32_e32 v125, 0xffff0000, v164
	v_exp_f32_e32 v5, v5
	v_mul_f32_e32 v126, 0xbfb8aa3b, v125
	v_exp_f32_e32 v127, v126
	s_waitcnt lgkmcnt(2)
	v_lshlrev_b32_e32 v128, 16, v110
	v_add_f32_e32 v5, 1.0, v5
	v_rcp_f32_e32 v126, v5
	v_add_f32_e32 v5, 1.0, v127
	v_rcp_f32_e32 v127, v5
	v_and_b32_e32 v129, 0xffff0000, v110
	v_pk_mul_f32 v[128:129], v[2:3], v[128:129] op_sel_hi:[0,1]
	v_pk_mul_f32 v[128:129], v[102:103], v[128:129]
	v_pk_mul_f32 v[124:125], v[126:127], v[124:125]
	v_mov_b64_e32 v[52:53], v[168:169]
	v_mov_b64_e32 v[54:55], v[170:171]
	v_mov_b64_e32 v[56:57], v[136:137]
	v_pk_mul_f32 v[124:125], v[124:125], v[128:129]
	v_lshlrev_b32_e32 v128, 16, v111
	v_cvt_pk_bf16_f32 v110, v124, v125
	v_lshlrev_b32_e32 v124, 16, v165
	v_mul_f32_e32 v5, 0xbfb8aa3b, v124
	v_and_b32_e32 v125, 0xffff0000, v165
	v_exp_f32_e32 v5, v5
	v_mul_f32_e32 v126, 0xbfb8aa3b, v125
	v_exp_f32_e32 v127, v126
	v_and_b32_e32 v129, 0xffff0000, v111
	v_add_f32_e32 v5, 1.0, v5
	v_rcp_f32_e32 v126, v5
	v_add_f32_e32 v5, 1.0, v127
	v_rcp_f32_e32 v127, v5
	v_pk_mul_f32 v[128:129], v[2:3], v[128:129] op_sel_hi:[0,1]
	v_pk_mul_f32 v[128:129], v[104:105], v[128:129]
	v_lshlrev_b32_e32 v170, 16, v156
	v_pk_mul_f32 v[124:125], v[126:127], v[124:125]
	v_and_b32_e32 v171, 0xffff0000, v156
	v_pk_mul_f32 v[124:125], v[124:125], v[128:129]
	v_lshlrev_b32_e32 v128, 16, v112
	v_cvt_pk_bf16_f32 v111, v124, v125
	v_lshlrev_b32_e32 v124, 16, v160
	v_mul_f32_e32 v5, 0xbfb8aa3b, v124
	v_and_b32_e32 v125, 0xffff0000, v160
	v_exp_f32_e32 v5, v5
	v_mul_f32_e32 v126, 0xbfb8aa3b, v125
	v_exp_f32_e32 v127, v126
	v_and_b32_e32 v129, 0xffff0000, v112
	v_add_f32_e32 v5, 1.0, v5
	v_rcp_f32_e32 v126, v5
	v_add_f32_e32 v5, 1.0, v127
	v_rcp_f32_e32 v127, v5
	v_pk_mul_f32 v[128:129], v[2:3], v[128:129] op_sel_hi:[0,1]
	v_pk_mul_f32 v[128:129], v[106:107], v[128:129]
	v_lshlrev_b32_e32 v160, 16, v158
	v_pk_mul_f32 v[124:125], v[126:127], v[124:125]
	s_nop 0
	v_pk_mul_f32 v[124:125], v[124:125], v[128:129]
	v_lshlrev_b32_e32 v128, 16, v113
	v_cvt_pk_bf16_f32 v112, v124, v125
	v_lshlrev_b32_e32 v124, 16, v161
	v_mul_f32_e32 v5, 0xbfb8aa3b, v124
	v_and_b32_e32 v125, 0xffff0000, v161
	v_exp_f32_e32 v5, v5
	v_mul_f32_e32 v126, 0xbfb8aa3b, v125
	v_exp_f32_e32 v127, v126
	v_and_b32_e32 v129, 0xffff0000, v113
	v_add_f32_e32 v5, 1.0, v5
	v_rcp_f32_e32 v126, v5
	v_add_f32_e32 v5, 1.0, v127
	v_rcp_f32_e32 v127, v5
	v_pk_mul_f32 v[128:129], v[2:3], v[128:129] op_sel_hi:[0,1]
	v_pk_mul_f32 v[128:129], v[108:109], v[128:129]
	v_and_b32_e32 v161, 0xffff0000, v158
	v_pk_mul_f32 v[124:125], v[126:127], v[124:125]
	v_mul_f32_e32 v5, 0xbfb8aa3b, v160
	v_pk_mul_f32 v[124:125], v[124:125], v[128:129]
	ds_read2_b32 v[128:129], v205 offset0:32 offset1:48
	ds_read2_b32 v[130:131], v205 offset0:160 offset1:176
	ds_read2_b32 v[132:133], v205 offset0:96 offset1:112
	ds_read2_b32 v[134:135], v205 offset0:224 offset1:240
	v_cvt_pk_bf16_f32 v113, v124, v125
	v_add_u32_e32 v124, 16, v4
	v_ashrrev_i32_e32 v125, 31, v124
	v_lshlrev_b64 v[124:125], 11, v[124:125]
	v_lshl_add_u64 v[124:125], v[150:151], 0, v[124:125]
	v_mov_b64_e32 v[58:59], v[110:111]
	v_mov_b64_e32 v[60:61], v[112:113]
	v_mov_b64_e32 v[62:63], v[124:125]
	v_exp_f32_e32 v5, v5
	v_add_u32_e32 v2, v204, v190
	s_waitcnt lgkmcnt(3)
	v_mov_b32_e32 v110, v128
	s_waitcnt lgkmcnt(2)
	v_mov_b32_e32 v111, v130
	s_waitcnt lgkmcnt(1)
	v_mov_b32_e32 v112, v132
	s_waitcnt lgkmcnt(0)
	v_mov_b32_e32 v113, v134
	v_pk_add_f32 v[136:137], v[110:111], v[112:113]
	v_mul_f32_e32 v110, 0xbfb8aa3b, v161
	v_exp_f32_e32 v124, v110
	ds_read_b128 v[110:113], v2
	v_add_f32_e32 v2, 1.0, v5
	v_rcp_f32_e32 v164, v2
	v_add_f32_e32 v2, 1.0, v124
	v_rcp_f32_e32 v165, v2
	v_add_u32_e32 v2, v204, v192
	v_lshlrev_b32_e32 v158, 16, v159
	ds_read_b128 v[124:127], v2
	v_mul_f32_e32 v2, 0xbfb8aa3b, v158
	v_and_b32_e32 v159, 0xffff0000, v159
	v_exp_f32_e32 v2, v2
	v_mul_f32_e32 v5, 0xbfb8aa3b, v159
	v_exp_f32_e32 v5, v5
	v_pk_mul_f32 v[160:161], v[164:165], v[160:161]
	v_add_f32_e32 v2, 1.0, v2
	v_rcp_f32_e32 v164, v2
	v_add_f32_e32 v2, 1.0, v5
	v_rcp_f32_e32 v165, v2
	v_mul_f32_e32 v2, 0xbfb8aa3b, v170
	v_exp_f32_e32 v2, v2
	v_mul_f32_e32 v5, 0xbfb8aa3b, v171
	v_exp_f32_e32 v5, v5
	v_lshlrev_b32_e32 v204, 16, v157
	v_add_f32_e32 v2, 1.0, v2
	v_rcp_f32_e32 v156, v2
	v_add_f32_e32 v2, 1.0, v5
	v_and_b32_e32 v205, 0xffff0000, v157
	v_mul_f32_e32 v5, 0xbfb8aa3b, v204
	v_pk_mul_f32 v[158:159], v[164:165], v[158:159]
	s_waitcnt lgkmcnt(1)
	v_lshlrev_b32_e32 v164, 16, v112
	v_and_b32_e32 v165, 0xffff0000, v112
	v_exp_f32_e32 v5, v5
	v_mul_f32_e32 v112, 0xbfb8aa3b, v205
	v_exp_f32_e32 v112, v112
	v_mov_b32_e32 v130, v129
	v_mov_b32_e32 v134, v133
	v_pk_add_f32 v[130:131], v[130:131], v[134:135]
	v_mov_b32_e32 v133, v136
	v_mov_b32_e32 v132, v130
	v_mov_b32_e32 v136, v131
	v_rcp_f32_e32 v157, v2
	v_add_f32_e32 v2, 1.0, v5
	v_pk_add_f32 v[130:131], v[132:133], v[136:137]
	v_rcp_f32_e32 v206, v2
	v_add_f32_e32 v2, 1.0, v112
	v_pk_fma_f32 v[122:123], v[130:131], s[14:15], v[122:123] op_sel_hi:[1,0,0]
	v_rcp_f32_e32 v207, v2
	v_mul_f32_e32 v2, 0x4b800000, v123
	v_cmp_gt_f32_e32 vcc, s51, v123
	v_lshlrev_b32_e32 v168, 16, v110
	v_and_b32_e32 v169, 0xffff0000, v110
	v_cndmask_b32_e32 v2, v123, v2, vcc
	v_rsq_f32_e32 v2, v2
	v_lshlrev_b32_e32 v110, 16, v111
	v_and_b32_e32 v111, 0xffff0000, v111
	v_lshlrev_b32_e32 v112, 16, v113
	v_mul_f32_e32 v5, 0x45800000, v2
	v_cndmask_b32_e32 v2, v2, v5, vcc
	v_pk_mul_f32 v[130:131], v[2:3], v[168:169] op_sel_hi:[0,1]
	v_pk_mul_f32 v[110:111], v[2:3], v[110:111] op_sel_hi:[0,1]
	v_pk_mul_f32 v[102:103], v[102:103], v[130:131]
	v_pk_mul_f32 v[104:105], v[104:105], v[110:111]
	v_pk_mul_f32 v[102:103], v[160:161], v[102:103]
	v_pk_mul_f32 v[104:105], v[158:159], v[104:105]
	v_and_b32_e32 v113, 0xffff0000, v113
	v_cvt_pk_bf16_f32 v102, v102, v103
	v_cvt_pk_bf16_f32 v103, v104, v105
	v_pk_mul_f32 v[104:105], v[2:3], v[164:165] op_sel_hi:[0,1]
	v_pk_mul_f32 v[104:105], v[106:107], v[104:105]
	v_pk_mul_f32 v[106:107], v[2:3], v[112:113] op_sel_hi:[0,1]
	v_mul_f32_e32 v2, 0x4b800000, v122
	v_cmp_gt_f32_e32 vcc, s51, v122
	v_add_u32_e32 v128, 32, v4
	v_pk_mul_f32 v[156:157], v[156:157], v[170:171]
	v_cndmask_b32_e32 v2, v122, v2, vcc
	v_rsq_f32_e32 v2, v2
	v_pk_mul_f32 v[170:171], v[206:207], v[204:205]
	v_ashrrev_i32_e32 v129, 31, v128
	v_pk_mul_f32 v[106:107], v[108:109], v[106:107]
	v_lshlrev_b64 v[128:129], 11, v[128:129]
	v_pk_mul_f32 v[104:105], v[156:157], v[104:105]
	v_pk_mul_f32 v[106:107], v[170:171], v[106:107]
	v_lshl_add_u64 v[128:129], v[150:151], 0, v[128:129]
	v_cvt_pk_bf16_f32 v104, v104, v105
	v_cvt_pk_bf16_f32 v105, v106, v107
	v_mov_b64_e32 v[64:65], v[102:103]
	v_mov_b64_e32 v[66:67], v[104:105]
	v_mov_b64_e32 v[68:69], v[128:129]
	v_mul_f32_e32 v5, 0x45800000, v2
	v_cndmask_b32_e32 v2, v2, v5, vcc
	v_lshlrev_b32_e32 v102, 16, v154
	v_mul_f32_e32 v5, 0xbfb8aa3b, v102
	v_and_b32_e32 v103, 0xffff0000, v154
	v_exp_f32_e32 v5, v5
	v_mul_f32_e32 v104, 0xbfb8aa3b, v103
	v_exp_f32_e32 v105, v104
	s_waitcnt lgkmcnt(0)
	v_lshlrev_b32_e32 v106, 16, v124
	v_add_f32_e32 v5, 1.0, v5
	v_rcp_f32_e32 v104, v5
	v_add_f32_e32 v5, 1.0, v105
	v_rcp_f32_e32 v105, v5
	v_and_b32_e32 v107, 0xffff0000, v124
	v_pk_mul_f32 v[106:107], v[2:3], v[106:107] op_sel_hi:[0,1]
	v_pk_mul_f32 v[106:107], v[118:119], v[106:107]
	v_pk_mul_f32 v[102:103], v[104:105], v[102:103]
	v_lshlrev_b32_e32 v104, 16, v155
	v_pk_mul_f32 v[102:103], v[102:103], v[106:107]
	v_mul_f32_e32 v5, 0xbfb8aa3b, v104
	v_and_b32_e32 v105, 0xffff0000, v155
	v_cvt_pk_bf16_f32 v102, v102, v103
	v_exp_f32_e32 v5, v5
	v_mul_f32_e32 v103, 0xbfb8aa3b, v105
	v_exp_f32_e32 v103, v103
	v_lshlrev_b32_e32 v108, 16, v125
	v_add_f32_e32 v5, 1.0, v5
	v_rcp_f32_e32 v106, v5
	v_add_f32_e32 v5, 1.0, v103
	v_rcp_f32_e32 v107, v5
	v_and_b32_e32 v109, 0xffff0000, v125
	v_pk_mul_f32 v[108:109], v[2:3], v[108:109] op_sel_hi:[0,1]
	v_pk_mul_f32 v[108:109], v[120:121], v[108:109]
	v_pk_mul_f32 v[104:105], v[106:107], v[104:105]
	v_lshlrev_b32_e32 v110, 16, v127
	v_pk_mul_f32 v[104:105], v[104:105], v[108:109]
	v_lshlrev_b32_e32 v108, 16, v126
	v_cvt_pk_bf16_f32 v103, v104, v105
	v_lshlrev_b32_e32 v104, 16, v152
	v_mul_f32_e32 v5, 0xbfb8aa3b, v104
	v_and_b32_e32 v105, 0xffff0000, v152
	v_exp_f32_e32 v5, v5
	v_mul_f32_e32 v106, 0xbfb8aa3b, v105
	v_exp_f32_e32 v107, v106
	v_and_b32_e32 v109, 0xffff0000, v126
	v_add_f32_e32 v5, 1.0, v5
	v_rcp_f32_e32 v106, v5
	v_add_f32_e32 v5, 1.0, v107
	v_rcp_f32_e32 v107, v5
	v_pk_mul_f32 v[108:109], v[2:3], v[108:109] op_sel_hi:[0,1]
	v_pk_mul_f32 v[108:109], v[114:115], v[108:109]
	v_and_b32_e32 v111, 0xffff0000, v127
	v_pk_mul_f32 v[104:105], v[106:107], v[104:105]
	v_lshlrev_b32_e32 v106, 16, v153
	v_pk_mul_f32 v[104:105], v[104:105], v[108:109]
	v_mul_f32_e32 v5, 0xbfb8aa3b, v106
	v_and_b32_e32 v107, 0xffff0000, v153
	v_cvt_pk_bf16_f32 v104, v104, v105
	v_exp_f32_e32 v5, v5
	v_mul_f32_e32 v105, 0xbfb8aa3b, v107
	v_exp_f32_e32 v105, v105
	v_pk_mul_f32 v[110:111], v[2:3], v[110:111] op_sel_hi:[0,1]
	v_add_f32_e32 v5, 1.0, v5
	v_rcp_f32_e32 v108, v5
	v_add_f32_e32 v5, 1.0, v105
	v_rcp_f32_e32 v109, v5
	v_add_u32_e32 v4, 48, v4
	v_pk_mul_f32 v[110:111], v[116:117], v[110:111]
	v_ashrrev_i32_e32 v5, 31, v4
	v_pk_mul_f32 v[106:107], v[108:109], v[106:107]
	v_lshlrev_b64 v[4:5], 11, v[4:5]
	v_pk_mul_f32 v[106:107], v[106:107], v[110:111]
	v_lshl_add_u64 v[4:5], v[150:151], 0, v[4:5]
	v_cvt_pk_bf16_f32 v105, v106, v107
	v_mov_b64_e32 v[70:71], v[102:103]
	v_mov_b64_e32 v[72:73], v[104:105]
	v_mov_b64_e32 v[74:75], v[4:5]
.LBB0_445:
	s_add_i32 s58, s29, 1
	s_cmpk_lg_i32 s56, 0xfc0
	s_cselect_b32 s31, s58, 63
	s_add_u32 s38, s34, s31
	v_mov_b32_e32 v106, v180
	s_addc_u32 s39, s35, 0
	s_bitcmp1_b32 s57, 0
	v_ashrrev_i32_e32 v107, 4, v106
	v_add_u32_e32 v2, s52, v107
	s_cselect_b32 s0, 0xe000, 0
	v_xor_b32_e32 v4, v2, v106
	s_add_i32 s37, s27, s0
	v_ashrrev_i32_e32 v108, 3, v106
	s_lshl_b64 s[0:1], s[38:39], 13
	s_lshl_b64 s[60:61], s[38:39], 14
	v_lshlrev_b32_e32 v2, 7, v2
	v_lshlrev_b32_e32 v4, 3, v4
	s_add_u32 s62, s43, s60
	v_and_or_b32 v2, v4, s50, v2
	v_add_u32_e32 v4, s53, v108
	s_addc_u32 s63, s44, s61
	v_lshrrev_b32_e32 v5, 1, v4
	s_add_u32 s64, s15, s60
	v_xor_b32_e32 v5, v5, v106
	s_addc_u32 s65, s19, s61
	s_add_i32 s59, s37, 0x4000
	v_lshlrev_b32_e32 v4, 6, v4
	v_lshlrev_b32_e32 v5, 3, v5
	v_lshlrev_b64 v[102:103], 1, v[2:3]
	s_add_u32 s60, s45, s60
	v_and_or_b32 v4, v5, 56, v4
	v_lshl_add_u64 v[104:105], s[62:63], 0, v[102:103]
	s_mov_b32 m0, s37
	v_mov_b32_e32 v5, v3
	s_addc_u32 s61, s46, s61
	s_add_i32 s66, s37, 0x8000
	global_load_lds_dwordx4 v[104:105], off
	v_lshl_add_u64 v[102:103], s[64:65], 0, v[102:103]
	s_mov_b32 m0, s59
	v_lshlrev_b64 v[4:5], 1, v[4:5]
	global_load_lds_dwordx4 v[102:103], off
	v_lshl_add_u64 v[102:103], s[60:61], 0, v[4:5]
	s_mov_b32 m0, s66
	v_add_u32_e32 v2, s54, v107
	global_load_lds_dwordx4 v[102:103], off
	v_xor_b32_e32 v102, v2, v106
	v_lshlrev_b32_e32 v2, 7, v2
	v_lshlrev_b32_e32 v102, 3, v102
	v_and_or_b32 v2, v102, s50, v2
	v_add_u32_e32 v102, s55, v108
	v_lshrrev_b32_e32 v103, 1, v102
	v_lshlrev_b64 v[104:105], 1, v[2:3]
	v_xor_b32_e32 v103, v103, v106
	v_lshl_add_u64 v[106:107], s[62:63], 0, v[104:105]
	s_add_i32 m0, s37, 0x2000
	v_lshlrev_b32_e32 v102, 6, v102
	v_lshlrev_b32_e32 v103, 3, v103
	global_load_lds_dwordx4 v[106:107], off
	v_lshl_add_u64 v[104:105], s[64:65], 0, v[104:105]
	s_add_i32 m0, s37, 0x6000
	v_and_or_b32 v102, v103, 56, v102
	global_load_lds_dwordx4 v[104:105], off
	v_mov_b32_e32 v103, v3
	s_add_i32 m0, s37, 0xa000
	v_lshl_add_u64 v[102:103], v[102:103], 1, s[60:61]
	s_add_u32 s0, s33, s0
	global_load_lds_dwordx4 v[102:103], off
	s_addc_u32 s1, s40, s1
	s_add_i32 m0, s37, 0xc000
	v_lshl_add_u64 v[4:5], s[0:1], 0, v[4:5]
	s_and_b64 s[0:1], s[24:25], exec
	s_cselect_b32 s0, s31, s29
	s_mul_hi_u32 s1, s26, s0
	s_mul_i32 s0, s26, s0
	global_load_lds_dwordx4 v[4:5], off
	v_lshl_add_u64 v[4:5], s[0:1], 1, v[162:163]
	s_mov_b32 s29, s9
	v_lshl_add_u64 v[102:103], v[4:5], 0, s[8:9]
	v_lshl_add_u64 v[104:105], v[4:5], 0, s[28:29]
	s_mov_b32 s37, s9
	s_mov_b32 s31, s9
	v_lshl_add_u64 v[106:107], v[104:105], 0, s[8:9]
	global_load_dwordx2 v[170:171], v[4:5], off
	global_load_dwordx2 v[168:169], v[102:103], off
	global_load_dwordx2 v[164:165], v[104:105], off
	global_load_dwordx2 v[160:161], v[106:107], off
	v_lshl_add_u64 v[102:103], v[4:5], 0, s[36:37]
	v_lshl_add_u64 v[4:5], v[4:5], 0, s[30:31]
	v_lshl_add_u64 v[104:105], v[102:103], 0, s[8:9]
	v_lshl_add_u64 v[106:107], v[4:5], 0, s[8:9]
	global_load_dwordx2 v[158:159], v[102:103], off
	global_load_dwordx2 v[156:157], v[104:105], off
	global_load_dwordx2 v[154:155], v[4:5], off
	global_load_dwordx2 v[152:153], v[106:107], off
	s_and_b64 vcc, exec, s[6:7]
	s_cbranch_vccnz .Lfin_stores
	s_lshl_b64 s[0:1], s[38:39], 2
	s_add_u32 s0, s41, s0
	s_addc_u32 s1, s42, s1
	global_load_dword v147, v3, s[0:1]
	s_branch .LBB0_447
.Lfin_stores:
	global_store_dwordx4 v[56:57], v[52:55], off
	global_store_dwordx4 v[62:63], v[58:61], off
	global_store_dwordx4 v[68:69], v[64:67], off
	global_store_dwordx4 v[74:75], v[70:73], off
